# phase-order stagger: odd workgroups run their gates GEMM tiles before the HBM-bound POST elementwise loops (even ones after), so memory-bound and MFMA-bound work overlap across the chip
# speedup vs baseline: 1.0035x; 1.0035x over previous
.LBB0_756:
	s_or_b64 exec, exec, s[0:1]
	v_mov_b32_e32 v12, v206
	v_readlane_b32 s0, v248, 23
	s_waitcnt lgkmcnt(0)
	s_barrier
	s_bitcmp1_b32 s72, 0
	s_cbranch_scc0 .Lpo_loops
	s_mov_b32 s101, 4
	s_mov_b64 s[0:1], exec
	s_branch .LBB0_762
.Lpo_back:
	s_mov_b32 s101, 5
	v_mov_b32_e32 v12, v206
	v_readlane_b32 s0, v248, 23
	s_nop 3
.Lpo_loops:
	s_mov_b64 s[6:7], s[70:71]
	v_add_u32_e32 v1, s0, v12
	s_mov_b32 s0, 0x100000
	v_cmp_gt_i32_e32 vcc, s0, v1
	s_and_saveexec_b64 s[0:1], vcc
	s_cbranch_execz .LBB0_759
	v_lshrrev_b32_e32 v2, 1, v12
	v_and_b32_e32 v8, 63, v12
	v_and_b32_e32 v2, 28, v2
	v_mov_b32_e32 v3, v0
	v_lshl_add_u64 v[2:3], s[6:7], 0, v[2:3]
	s_mov_b64 s[2:3], 0x11600000
	v_lshlrev_b32_e32 v8, 4, v8
	v_mov_b32_e32 v9, v0
	v_lshl_add_u64 v[2:3], v[2:3], 0, s[2:3]
	v_lshl_add_u64 v[10:11], s[6:7], 0, v[8:9]
	s_mov_b64 s[2:3], 0x1a800000
	v_lshl_add_u64 v[8:9], v[10:11], 0, s[2:3]
	s_mov_b64 s[2:3], 0x11800000
	v_lshl_add_u64 v[10:11], v[10:11], 0, s[2:3]
	s_mov_b64 s[2:3], 0
	v_mov_b32_e32 v13, v1

.LBB0_762:
	s_or_b64 exec, exec, s[0:1]
	s_cmp_eq_u32 s101, 5
	s_cbranch_scc0 .Lpo_gates
	s_mov_b32 s101, 0
	s_branch .LBB0_778
.Lpo_gates:
	v_readlane_b32 s0, v249, 56
	s_mov_b64 s[2:3], s[70:71]
	v_mov_b32_e32 v22, v206
	v_readlane_b32 s1, v249, 57
	s_andn2_b64 vcc, exec, s[0:1]
	v_readfirstlane_b32 s4, v22
	s_cbranch_vccnz .LBB0_778
	v_lshlrev_b32_e32 v1, 4, v22
	v_add_u32_e32 v2, 0x2000, v1
	v_ashrrev_i32_e32 v3, 31, v2
	v_lshrrev_b32_e32 v3, 22, v3
	v_add_u32_e32 v3, v2, v3
	v_ashrrev_i32_e32 v16, 10, v3
	v_mul_i32_i24_e32 v3, 0x400, v16
	v_sub_u32_e32 v2, v2, v3
	v_lshrrev_b32_e32 v3, 4, v2
	v_bitop3_b32 v2, v3, v2, 32 bitop3:0x6c
	v_ashrrev_i32_e32 v3, 31, v2
	v_readlane_b32 s0, v252, 7
	v_lshrrev_b32_e32 v3, 26, v3
	s_lshl_b32 s0, s0, 25
	v_add_u32_e32 v3, v2, v3
	v_lshlrev_b32_e32 v8, 3, v16
	s_add_u32 s0, s2, s0
	v_ashrrev_i32_e32 v17, 6, v3
	v_and_b32_e32 v8, -16, v8
	s_addc_u32 s1, s3, 0
	v_add_u32_e32 v8, v17, v8
	s_add_u32 s20, s0, 0x2c00000
	v_and_b32_e32 v9, 3, v17
	s_mov_b32 s0, 0x1fffe0
	v_lshrrev_b32_e32 v10, 2, v8
	v_lshlrev_b32_e32 v11, 1, v8
	v_and_b32_e32 v3, 0xc0, v3
	v_and_or_b32 v9, v8, s0, v9
	v_and_b32_e32 v10, 4, v10
	v_and_b32_e32 v11, 24, v11
	v_sub_u32_e32 v2, v2, v3
	v_or3_b32 v9, v9, v10, v11
	v_lshlrev_b32_e32 v10, 5, v16
	v_ashrrev_i16_sdwa v2, v209, sext(v2) dst_sel:DWORD dst_unused:UNUSED_PAD src0_sel:DWORD src1_sel:BYTE_0
	v_and_b32_e32 v10, 32, v10
	v_bfe_i32 v18, v2, 0, 16
	v_add_lshl_u32 v3, v10, v18, 1
	v_lshl_add_u32 v2, v9, 11, v3
	v_lshl_add_u32 v168, v8, 11, v3
	v_bfe_i32 v3, v22, 27, 1
	v_lshrrev_b32_e32 v3, 22, v3
	v_add_u32_e32 v3, v1, v3
	v_and_b32_e32 v3, 0xfffffc00, v3
	v_sub_u32_e32 v1, v1, v3
	v_lshrrev_b32_e32 v3, 4, v1
	v_ashrrev_i32_e32 v8, 31, v22
	v_bitop3_b32 v1, v3, v1, 32 bitop3:0x6c
	v_lshrrev_b32_e32 v8, 26, v8
	v_ashrrev_i32_e32 v3, 31, v1
	v_add_u32_e32 v8, v22, v8
	v_lshrrev_b32_e32 v3, 26, v3
	v_ashrrev_i32_e32 v20, 6, v8
	v_add_u32_e32 v3, v1, v3
	v_lshlrev_b32_e32 v8, 3, v20
	v_ashrrev_i32_e32 v19, 6, v3
	v_and_b32_e32 v8, -16, v8
	s_addc_u32 s21, s1, 0
	v_add_u32_e32 v8, v19, v8
	s_add_u32 s22, s2, 0xe00000
	v_and_b32_e32 v9, 3, v19
	v_lshrrev_b32_e32 v10, 2, v8
	v_lshlrev_b32_e32 v11, 1, v8
	v_and_b32_e32 v3, 0xc0, v3
	s_addc_u32 s23, s3, 0
	s_ashr_i32 s5, s4, 6
	v_and_or_b32 v9, v8, s0, v9
	v_and_b32_e32 v10, 4, v10
	v_and_b32_e32 v11, 24, v11
	v_sub_u32_e32 v1, v1, v3
	s_ashr_i32 s6, s4, 8
	s_lshl_b32 s24, s5, 10
	v_or3_b32 v9, v9, v10, v11
	v_lshlrev_b32_e32 v10, 5, v20
	v_ashrrev_i16_sdwa v1, v209, sext(v1) dst_sel:DWORD dst_unused:UNUSED_PAD src0_sel:DWORD src1_sel:BYTE_0
	v_readlane_b32 s0, v249, 59
	v_and_b32_e32 v10, 32, v10
	v_bfe_i32 v21, v1, 0, 16
	v_readlane_b32 s1, v249, 60
	s_add_u32 s14, s22, s0
	v_add_lshl_u32 v1, v10, v21, 1
	s_addc_u32 s15, s23, s1
	s_add_i32 s25, s24, 0
	v_lshl_add_u32 v170, v9, 11, v1
	s_add_i32 m0, s25, 0x10000
	v_lshl_add_u32 v172, v8, 11, v1
	global_load_lds_dwordx4 v170, s[14:15]
	s_add_i32 m0, s25, 0x12000
	s_add_u32 s0, s14, 0x40000
	global_load_lds_dwordx4 v2, s[14:15]
	s_addc_u32 s1, s15, 0
	s_add_i32 m0, s25, 0x14000
	v_mov_b32_e32 v171, v0
	global_load_lds_dwordx4 v170, s[0:1]
	s_add_i32 m0, s25, 0x16000
	v_mov_b32_e32 v3, v0
	global_load_lds_dwordx4 v2, s[0:1]
	v_readlane_b32 s0, v249, 63
	v_readlane_b32 s1, v250, 0
	s_add_u32 s16, s20, s0
	s_addc_u32 s17, s21, s1
	s_add_i32 s26, s25, 0x2000
	s_mov_b32 m0, s25
	s_add_u32 s0, s16, 0x40000
	global_load_lds_dwordx4 v172, s[16:17]
	s_mov_b32 m0, s26
	s_addc_u32 s1, s17, 0
	s_add_i32 s27, s25, 0x4000
	global_load_lds_dwordx4 v168, s[16:17]
	s_mov_b32 m0, s27
	s_add_i32 s28, s25, 0x6000
	global_load_lds_dwordx4 v172, s[0:1]
	s_mov_b32 m0, s28
	v_mov_b32_e32 v173, v0
	global_load_lds_dwordx4 v168, s[0:1]
	v_mov_b32_e32 v169, v0
	s_cmp_eq_u32 s6, 1
	v_lshl_add_u64 v[14:15], s[14:15], 0, v[170:171]
	v_lshl_add_u64 v[12:13], s[14:15], 0, v[2:3]
	v_lshl_add_u64 v[8:9], s[16:17], 0, v[172:173]
	s_cselect_b64 s[0:1], -1, 0
	s_cmp_lg_u32 s6, 1
	v_lshl_add_u64 v[10:11], s[16:17], 0, v[168:169]
	s_cbranch_scc1 .LBB0_765
	s_barrier

.LBB0_778:
	s_cmp_eq_u32 s101, 4
	s_cbranch_scc1 .Lpo_back
	s_cmp_eq_u32 s101, 3
	s_cbranch_scc1 .Lgt_ret
	s_waitcnt vmcnt(0)
	s_barrier
	s_mov_b64 s[0:1], exec
	v_readlane_b32 s2, v248, 18
	v_readlane_b32 s3, v248, 19
	s_and_b64 s[2:3], s[0:1], s[2:3]
	s_mov_b64 exec, s[2:3]
	s_cbranch_execz .LBB0_830
	v_readlane_b32 s2, v251, 2
	s_waitcnt vmcnt(0) expcnt(0) lgkmcnt(0)
	s_nop 0
	v_mov_b32_e32 v1, s2
	ds_read_b32 v3, v1
	v_readlane_b32 s2, v251, 3
	s_waitcnt lgkmcnt(0)
	v_cmp_ne_u32_e32 vcc, 0, v3
	v_mov_b32_e32 v1, s2
	ds_read_b32 v2, v1
	s_cbranch_vccnz .LBB0_794
	s_mov_b32 s8, 1
	s_branch .LBB0_782
